# attention: per-tile barrier moved from tile boundary into the exp block (after last LDS read + next-tile staging); loop-top barrier first entry only
# baseline (speedup 1.0000x reference)
; template <int MODE> ...
;     ...
;   for (int it = 0; it < ntile; ++it) {
;     const int kt0 = (it < na) ? ka0 + it * 64 : kb0 + (it - na) * 64;
;     const bool masked = window && (it < na);
;     const u16* Ks = Kbase + (it & 1) * (2 * 64 * 64);
;     const u16* Vs = Ks + 64 * 64;
;     __syncthreads();
;     const bool more = it + 1 < ntile;
;     if (more) {
;       const int kn = (it + 1 < na) ? ka0 + (it + 1) * 64 : kb0 + (it + 1 - na) * 64;
;       ALOAD(kn)
;     }
;     bool skip = false;
;     if (masked) {
;       const int qlo = qtok0 + __builtin_amdgcn_readfirstlane(w) * 32;
;       skip = (kt0 > qlo + 31 + 128) || (kt0 + 63 < qlo - 128);
;     }
;     if (!skip) {
;     f32x4 S[2][2][2][2];
; #pragma unroll
;     for (int kh = 0; kh < 2; ++kh) {
;       bf16x8 kf[2][2];
; #pragma unroll
;       for (int t = 0; t < 2; ++t)
; #pragma unroll
;         for (int s2 = 0; s2 < 2; ++s2)
;           kf[t][s2] = *(const bf16x8*)&Ks[(kh * 32 + t * 16 + r) * 64 + (((s2 * 4 + g) ^ (r & 7)) * 8)];
.LBB0_862:
	s_waitcnt lgkmcnt(0)
	s_barrier
.Lattn1_top:
	s_add_i32 s66, s58, 1
	s_cmp_lt_i32 s66, s45
	s_cselect_b64 s[56:57], -1, 0
	s_add_i32 s98, s2, 0xffffe000
	s_and_b32 s98, s98, 0x2000
	v_lshl_add_u32 v0, s98, 1, v233
	v_add_u32_e32 v234, v0, v230
	v_add_u32_e32 v0, v0, v231
	ds_read_b128 v[108:111], v234
	ds_read_b128 v[112:115], v234 offset:2048
	ds_read_b128 v[120:123], v0
	ds_read_b128 v[132:135], v0 offset:2048
	s_cmp_ge_i32 s66, s45
	s_cbranch_scc1 .LBB0_864
	s_cmp_lt_i32 s66, s63
	s_cselect_b32 s59, 0, s63
	s_cselect_b32 s60, s64, 0x800
	s_lshl_b32 s59, s59, 6
	s_sub_i32 s59, s60, s59
	s_add_i32 s60, s65, s59
	s_ashr_i32 s61, s60, 31
	s_lshl_b64 s[68:69], s[60:61], 7
	s_waitcnt vmcnt(1)
	v_lshl_add_u64 v[100:101], v[182:183], 0, s[68:69]
	s_waitcnt vmcnt(0)
	v_lshl_add_u64 v[104:105], s[60:61], 1, v[184:185]
	global_load_dwordx4 v[100:103], v[100:101], off
	s_nop 0
	global_load_dwordx4 v[104:107], v[104:105], off

; template <int MODE> ...
;     ...
;     if (more) {
;       u16* Kn = Kbase + ((it + 1) & 1) * (2 * 64 * 64);
;       *(uint4*)&Kn[kwoff] = kr0;
;       *(uint4*)&Kn[64 * 64 + vwoff] = vr0;
;     }
.LBB0_867:
	s_and_b32 s56, s2, 0x2000
	s_lshl_b32 s56, s56, 1
	s_add_i32 s56, s56, 32
	v_lshl_add_u32 v108, v3, 1, s56
	v_lshl_add_u32 v0, v229, 1, s56
	s_waitcnt vmcnt(1)
	ds_write_b128 v108, v[100:103]
	s_waitcnt vmcnt(0)
	ds_write_b128 v0, v[104:107] offset:8192
	s_waitcnt lgkmcnt(0)
	s_barrier

; template <int MODE> ...
;     ...
;     }
;     if (more) {
;       u16* Kn = Kbase + ((it + 1) & 1) * (2 * 64 * 64);
;       *(uint4*)&Kn[kwoff] = kr0;
;       *(uint4*)&Kn[64 * 64 + vwoff] = vr0;
;     }
;   }
.Lattn1_skipexit:
	s_barrier
	s_branch .LBB0_874

; #define MFMA(a, b, c) __builtin_amdgcn_mfma_f32_16x16x32_bf16((a), (b), (c), 0, 0, 0)
; template <int MODE> ...
;     ...
; #pragma unroll
;     for (int kh = 0; kh < 2; ++kh) {
; #pragma unroll
;       for (int tt = 0; tt < 2; ++tt) {
;         bf16x8 pf[2];
; #pragma unroll
;         for (int hh = 0; hh < 2; ++hh) {
;           float pv[8];
; #pragma unroll
;           for (int j = 0; j < 4; ++j) {
;             pv[j] = __builtin_amdgcn_exp2f(S[kh][tt][hh][0][j]);
;             pv[4 + j] = __builtin_amdgcn_exp2f(S[kh][tt][hh][1][j]);
;           }
;           lsum[tt][hh] += ((pv[0] + pv[1]) + (pv[2] + pv[3])) + ((pv[4] + pv[5]) + (pv[6] + pv[7]));
;           const uint4 pk = make_uint4(pack2(pv[0], pv[1]), pack2(pv[2], pv[3]), pack2(pv[4], pv[5]), pack2(pv[6], pv[7]));
;           pf[hh] = __builtin_bit_cast(bf16x8, pk);
;         }
; #pragma unroll
;         for (int dt = 0; dt < 4; ++dt) {
;           const bf16x8 vf = *(const bf16x8*)&Vs[(dt * 16 + r) * 64 + (((kh * 4 + g) ^ (r & 7)) * 8)];
;           O[tt][0][dt] = MFMA(vf, pf[0], O[tt][0][dt]);
;           O[tt][1][dt] = MFMA(vf, pf[1], O[tt][1][dt]);
;         }
;       }
;     }
.Lattn1_nw:
	v_exp_f32_e32 v135, v140
	v_exp_f32_e32 v131, v144
	v_exp_f32_e32 v139, v141
	v_exp_f32_e32 v137, v145
	v_exp_f32_e32 v124, v164
	v_exp_f32_e32 v128, v165
	v_exp_f32_e32 v130, v166
	v_exp_f32_e32 v136, v167
	v_pk_add_f32 v[248:249], v[132:133], v[126:127]
	v_pk_add_f32 v[250:251], v[138:139], v[134:135]
	v_pk_add_f32 v[248:249], v[250:251], v[248:249]
	v_pk_add_f32 v[250:251], v[128:129], v[124:125]
	v_pk_add_f32 v[252:253], v[136:137], v[130:131]
	v_pk_add_f32 v[250:251], v[252:253], v[250:251]
	v_pk_add_f32 v[248:249], v[250:251], v[248:249]
	v_pk_add_f32 v[188:189], v[248:249], v[188:189]
	v_cvt_pk_bf16_f32 v240, v126, v132
	v_cvt_pk_bf16_f32 v241, v134, v138
	v_cvt_pk_bf16_f32 v242, v124, v128
	v_cvt_pk_bf16_f32 v243, v130, v136
	v_cvt_pk_bf16_f32 v244, v127, v133
	v_cvt_pk_bf16_f32 v245, v135, v139
	v_cvt_pk_bf16_f32 v246, v125, v129
	v_cvt_pk_bf16_f32 v247, v131, v137
	s_waitcnt lgkmcnt(0)
	s_barrier
	v_mfma_f32_16x16x32_bf16 v[52:55], v[208:211], v[240:243], v[52:55]
	v_exp_f32_e32 v148, v148
	v_mfma_f32_16x16x32_bf16 v[60:63], v[212:215], v[240:243], v[60:63]
	v_exp_f32_e32 v146, v152
	v_mfma_f32_16x16x32_bf16 v[56:59], v[216:219], v[240:243], v[56:59]
	v_exp_f32_e32 v152, v153
	v_mfma_f32_16x16x32_bf16 v[64:67], v[220:223], v[240:243], v[64:67]
	v_exp_f32_e32 v145, v163
	v_mfma_f32_16x16x32_bf16 v[44:47], v[208:211], v[244:247], v[44:47]
	v_exp_f32_e32 v141, v162
	v_mfma_f32_16x16x32_bf16 v[40:43], v[212:215], v[244:247], v[40:43]
	v_exp_f32_e32 v147, v160
	v_mfma_f32_16x16x32_bf16 v[36:39], v[216:219], v[244:247], v[36:39]
	v_exp_f32_e32 v153, v161
	v_mfma_f32_16x16x32_bf16 v[48:51], v[220:223], v[244:247], v[48:51]
	v_exp_f32_e32 v142, v150
	v_exp_f32_e32 v140, v154
	v_exp_f32_e32 v150, v151
	v_exp_f32_e32 v144, v155
	v_exp_f32_e32 v154, v149
	v_exp_f32_e32 v143, v158
	v_exp_f32_e32 v151, v159
	v_exp_f32_e32 v149, v156
	v_exp_f32_e32 v155, v157
	v_pk_add_f32 v[248:249], v[150:151], v[142:143]
	v_pk_add_f32 v[250:251], v[154:155], v[148:149]
	v_pk_add_f32 v[248:249], v[250:251], v[248:249]
	v_pk_add_f32 v[250:251], v[144:145], v[140:141]
	v_pk_add_f32 v[252:253], v[152:153], v[146:147]
	v_pk_add_f32 v[250:251], v[252:253], v[250:251]
	v_pk_add_f32 v[248:249], v[250:251], v[248:249]
	v_pk_add_f32 v[186:187], v[248:249], v[186:187]
	v_cvt_pk_bf16_f32 v240, v142, v150
	v_cvt_pk_bf16_f32 v241, v148, v154
	v_cvt_pk_bf16_f32 v242, v140, v144
	v_cvt_pk_bf16_f32 v243, v146, v152
	v_cvt_pk_bf16_f32 v244, v143, v151
	v_cvt_pk_bf16_f32 v245, v149, v155
	v_cvt_pk_bf16_f32 v246, v141, v145
	v_cvt_pk_bf16_f32 v247, v147, v153
	v_mfma_f32_16x16x32_bf16 v[32:35], v[208:211], v[240:243], v[32:35]
	v_mfma_f32_16x16x32_bf16 v[28:31], v[212:215], v[240:243], v[28:31]
	v_mfma_f32_16x16x32_bf16 v[24:27], v[216:219], v[240:243], v[24:27]
	v_mfma_f32_16x16x32_bf16 v[20:23], v[220:223], v[240:243], v[20:23]
	v_mfma_f32_16x16x32_bf16 v[16:19], v[208:211], v[244:247], v[16:19]
	v_mfma_f32_16x16x32_bf16 v[12:15], v[212:215], v[244:247], v[12:15]
	v_mfma_f32_16x16x32_bf16 v[8:11], v[216:219], v[244:247], v[8:11]
	v_mfma_f32_16x16x32_bf16 v[4:7], v[220:223], v[244:247], v[4:7]
	s_andn2_b64 vcc, exec, s[56:57]
	s_cbranch_vccz .Lattn1_adv

; template <int MODE> ...
;     ...
;   for (int it = 0; it < ntile; ++it) {
;     const int kt0 = (it < na) ? ka0 + it * 64 : kb0 + (it - na) * 64;
;     const bool masked = window && (it < na);
;     const u16* Ks = Kbase + (it & 1) * (2 * 64 * 64);
;     const u16* Vs = Ks + 64 * 64;
;     __syncthreads();
;     const bool more = it + 1 < ntile;
;     if (more) {
;       const int kn = (it + 1 < na) ? ka0 + (it + 1) * 64 : kb0 + (it + 1 - na) * 64;
;       ALOAD(kn)
;     }
;     bool skip = false;
;     if (masked) {
;       const int qlo = qtok0 + __builtin_amdgcn_readfirstlane(w) * 32;
;       skip = (kt0 > qlo + 31 + 128) || (kt0 + 63 < qlo - 128);
;     }
;     if (!skip) {
;     f32x4 S[2][2][2][2];
; #pragma unroll
;     for (int kh = 0; kh < 2; ++kh) {
;       bf16x8 kf[2][2];
; #pragma unroll
;       for (int t = 0; t < 2; ++t)
; #pragma unroll
;         for (int s2 = 0; s2 < 2; ++s2)
;           kf[t][s2] = *(const bf16x8*)&Ks[(kh * 32 + t * 16 + r) * 64 + (((s2 * 4 + g) ^ (r & 7)) * 8)];
.Lattn2_top:
	s_add_i32 s54, s50, 1
	s_cmp_lt_i32 s54, s24
	s_cselect_b64 s[48:49], -1, 0
	s_add_i32 s98, s2, 0xffffe000
	s_and_b32 s98, s98, 0x2000
	v_lshl_add_u32 v98, s98, 1, v196
	v_add_u32_e32 v198, v98, v191
	v_add_u32_e32 v197, v98, v192
	ds_read_b128 v[90:93], v198
	ds_read_b128 v[94:97], v198 offset:2048
	ds_read_b128 v[98:101], v197
	ds_read_b128 v[102:105], v197 offset:2048
	s_cmp_ge_i32 s54, s24
	s_cbranch_scc1 .LBB0_884
	s_cmp_lt_i32 s54, s63
	s_cselect_b32 s51, 0, s63
	s_cselect_b32 s52, s64, 0x800
	s_lshl_b32 s51, s51, 6
	s_sub_i32 s51, s52, s51
	s_add_i32 s52, s45, s51
	s_ashr_i32 s53, s52, 31
	s_lshl_b64 s[56:57], s[52:53], 7
	s_waitcnt vmcnt(1)
	v_lshl_add_u64 v[50:51], v[166:167], 0, s[56:57]
	s_waitcnt vmcnt(0)
	v_lshl_add_u64 v[54:55], s[52:53], 1, v[168:169]
	global_load_dwordx4 v[50:53], v[50:51], off
	s_nop 0
	global_load_dwordx4 v[54:57], v[54:55], off

; template <int MODE> ...
;     ...
;     if (more) {
;       u16* Kn = Kbase + ((it + 1) & 1) * (2 * 64 * 64);
;       *(uint4*)&Kn[kwoff] = kr0;
;       *(uint4*)&Kn[64 * 64 + vwoff] = vr0;
;     }
.LBB0_887:
	s_and_b32 s48, s2, 0x2000
	s_lshl_b32 s48, s48, 1
	s_add_i32 s48, s48, 32
	v_lshl_add_u32 v91, v165, 1, s48
	v_lshl_add_u32 v90, v190, 1, s48
	s_waitcnt vmcnt(1)
	ds_write_b128 v91, v[50:53]
	s_waitcnt vmcnt(0)
	ds_write_b128 v90, v[54:57] offset:8192
	s_waitcnt lgkmcnt(0)
	s_barrier

; #define MFMA(a, b, c) __builtin_amdgcn_mfma_f32_16x16x32_bf16((a), (b), (c), 0, 0, 0)
; template <int MODE> ...
;     ...
; #pragma unroll
;     for (int kh = 0; kh < 2; ++kh) {
; #pragma unroll
;       for (int tt = 0; tt < 2; ++tt) {
;         bf16x8 pf[2];
; #pragma unroll
;         for (int hh = 0; hh < 2; ++hh) {
;           float pv[8];
; #pragma unroll
;           for (int j = 0; j < 4; ++j) {
;             pv[j] = __builtin_amdgcn_exp2f(S[kh][tt][hh][0][j]);
;             pv[4 + j] = __builtin_amdgcn_exp2f(S[kh][tt][hh][1][j]);
;           }
;           lsum[tt][hh] += ((pv[0] + pv[1]) + (pv[2] + pv[3])) + ((pv[4] + pv[5]) + (pv[6] + pv[7]));
;           const uint4 pk = make_uint4(pack2(pv[0], pv[1]), pack2(pv[2], pv[3]), pack2(pv[4], pv[5]), pack2(pv[6], pv[7]));
;           pf[hh] = __builtin_bit_cast(bf16x8, pk);
;         }
; #pragma unroll
;         for (int dt = 0; dt < 4; ++dt) {
;           const bf16x8 vf = *(const bf16x8*)&Vs[(dt * 16 + r) * 64 + (((kh * 4 + g) ^ (r & 7)) * 8)];
;           O[tt][0][dt] = MFMA(vf, pf[0], O[tt][0][dt]);
;           O[tt][1][dt] = MFMA(vf, pf[1], O[tt][1][dt]);
;         }
;       }
;     }
.Lattn2_nw:
	v_exp_f32_e32 v117, v122
	v_exp_f32_e32 v113, v126
	v_exp_f32_e32 v121, v123
	v_exp_f32_e32 v119, v127
	v_exp_f32_e32 v106, v146
	v_exp_f32_e32 v110, v147
	v_exp_f32_e32 v112, v148
	v_exp_f32_e32 v118, v149
	v_pk_add_f32 v[248:249], v[114:115], v[108:109]
	v_pk_add_f32 v[250:251], v[120:121], v[116:117]
	v_pk_add_f32 v[248:249], v[250:251], v[248:249]
	v_pk_add_f32 v[250:251], v[110:111], v[106:107]
	v_pk_add_f32 v[252:253], v[118:119], v[112:113]
	v_pk_add_f32 v[250:251], v[252:253], v[250:251]
	v_pk_add_f32 v[248:249], v[250:251], v[248:249]
	v_pk_add_f32 v[170:171], v[248:249], v[170:171]
	v_cvt_pk_bf16_f32 v240, v108, v114
	v_cvt_pk_bf16_f32 v241, v116, v120
	v_cvt_pk_bf16_f32 v242, v106, v110
	v_cvt_pk_bf16_f32 v243, v112, v118
	v_cvt_pk_bf16_f32 v244, v109, v115
	v_cvt_pk_bf16_f32 v245, v117, v121
	v_cvt_pk_bf16_f32 v246, v107, v111
	v_cvt_pk_bf16_f32 v247, v113, v119
	s_waitcnt lgkmcnt(0)
	s_barrier
	v_mfma_f32_16x16x32_bf16 v[70:73], v[200:203], v[240:243], v[70:73]
	v_exp_f32_e32 v130, v130
	v_mfma_f32_16x16x32_bf16 v[78:81], v[204:207], v[240:243], v[78:81]
	v_exp_f32_e32 v128, v134
	v_mfma_f32_16x16x32_bf16 v[62:65], v[208:211], v[240:243], v[62:65]
	v_exp_f32_e32 v134, v135
	v_mfma_f32_16x16x32_bf16 v[74:77], v[212:215], v[240:243], v[74:77]
	v_exp_f32_e32 v127, v145
	v_mfma_f32_16x16x32_bf16 v[86:89], v[200:203], v[244:247], v[86:89]
	v_exp_f32_e32 v123, v144
	v_mfma_f32_16x16x32_bf16 v[66:69], v[204:207], v[244:247], v[66:69]
	v_exp_f32_e32 v129, v142
	v_mfma_f32_16x16x32_bf16 v[58:61], v[208:211], v[244:247], v[58:61]
	v_exp_f32_e32 v135, v143
	v_mfma_f32_16x16x32_bf16 v[82:85], v[212:215], v[244:247], v[82:85]
	v_exp_f32_e32 v124, v132
	v_exp_f32_e32 v122, v136
	v_exp_f32_e32 v132, v133
	v_exp_f32_e32 v126, v137
	v_exp_f32_e32 v136, v131
	v_exp_f32_e32 v125, v140
	v_exp_f32_e32 v133, v141
	v_exp_f32_e32 v131, v138
	v_exp_f32_e32 v137, v139
	v_pk_add_f32 v[248:249], v[132:133], v[124:125]
	v_pk_add_f32 v[250:251], v[136:137], v[130:131]
	v_pk_add_f32 v[248:249], v[250:251], v[248:249]
	v_pk_add_f32 v[250:251], v[126:127], v[122:123]
	v_pk_add_f32 v[252:253], v[134:135], v[128:129]
	v_pk_add_f32 v[250:251], v[252:253], v[250:251]
	v_pk_add_f32 v[248:249], v[250:251], v[248:249]
	v_pk_add_f32 v[156:157], v[248:249], v[156:157]
	v_cvt_pk_bf16_f32 v240, v124, v132
	v_cvt_pk_bf16_f32 v241, v130, v136
	v_cvt_pk_bf16_f32 v242, v122, v126
	v_cvt_pk_bf16_f32 v243, v128, v134
	v_cvt_pk_bf16_f32 v244, v125, v133
	v_cvt_pk_bf16_f32 v245, v131, v137
	v_cvt_pk_bf16_f32 v246, v123, v127
	v_cvt_pk_bf16_f32 v247, v129, v135
	v_mfma_f32_16x16x32_bf16 v[42:45], v[200:203], v[240:243], v[42:45]
	v_mfma_f32_16x16x32_bf16 v[34:37], v[204:207], v[240:243], v[34:37]
	v_mfma_f32_16x16x32_bf16 v[10:13], v[208:211], v[240:243], v[10:13]
	v_mfma_f32_16x16x32_bf16 v[6:9], v[212:215], v[240:243], v[6:9]
	v_mfma_f32_16x16x32_bf16 v[46:49], v[200:203], v[244:247], v[46:49]
	v_mfma_f32_16x16x32_bf16 v[38:41], v[204:207], v[244:247], v[38:41]
	v_mfma_f32_16x16x32_bf16 v[14:17], v[208:211], v[244:247], v[14:17]
	v_mfma_f32_16x16x32_bf16 v[2:5], v[212:215], v[244:247], v[2:5]
	s_andn2_b64 vcc, exec, s[48:49]
	s_cbranch_vccz .Lattn2_adv
